# P1 q/k epilogue: the 16 row-sum lane exchanges are batched (4 LDS round trips instead of 32)
# baseline (speedup 1.0000x reference)
.LBB0_133:
	v_mul_f32_e32 v143, v125, v125
	v_mul_f32_e32 v144, v127, v127
	v_and_b32_e32 v142, 64, v164
	v_fmac_f32_e32 v143, v124, v124
	v_fmac_f32_e32 v144, v126, v126
	v_xor_b32_e32 v132, 16, v164
	v_add_u32_e32 v142, 64, v142
	v_add_f32_e32 v143, v143, v144
	v_mul_f32_e32 v144, v121, v121
	v_mul_f32_e32 v145, v123, v123
	v_cmp_lt_i32_e32 vcc, v132, v142
	v_fmac_f32_e32 v144, v120, v120
	v_fmac_f32_e32 v145, v122, v122
	v_cndmask_b32_e32 v132, v164, v132, vcc
	v_add_f32_e32 v144, v144, v145
	v_lshlrev_b32_e32 v132, 2, v132
	v_add_f32_e32 v143, v143, v144
	v_mov_b32_e32 v196, v143
	v_xor_b32_e32 v145, 32, v164
	v_cmp_lt_i32_e32 vcc, v145, v142
	v_cndmask_b32_e32 v142, v164, v145, vcc
	v_lshlrev_b32_e32 v142, 2, v142
	v_mul_f32_e32 v143, v117, v117
	s_waitcnt lgkmcnt(0)
	v_mul_f32_e32 v144, v119, v119
	v_fmac_f32_e32 v143, v116, v116
	v_fmac_f32_e32 v144, v118, v118
	v_add_f32_e32 v143, v143, v144
	v_mul_f32_e32 v144, v113, v113
	v_mul_f32_e32 v145, v115, v115
	v_fmac_f32_e32 v144, v112, v112
	v_fmac_f32_e32 v145, v114, v114
	v_add_f32_e32 v144, v144, v145
	v_add_f32_e32 v143, v143, v144
	v_mov_b32_e32 v197, v143
	v_mul_f32_e32 v143, v109, v109
	s_waitcnt lgkmcnt(0)
	v_mul_f32_e32 v144, v111, v111
	v_fmac_f32_e32 v143, v108, v108
	v_fmac_f32_e32 v144, v110, v110
	v_add_f32_e32 v143, v143, v144
	v_mul_f32_e32 v144, v105, v105
	v_mul_f32_e32 v145, v107, v107
	v_fmac_f32_e32 v144, v104, v104
	v_fmac_f32_e32 v145, v106, v106
	v_add_f32_e32 v144, v144, v145
	v_add_f32_e32 v143, v143, v144
	v_mov_b32_e32 v198, v143
	v_mul_f32_e32 v143, v101, v101
	s_waitcnt lgkmcnt(0)
	v_mul_f32_e32 v144, v103, v103
	v_fmac_f32_e32 v143, v100, v100
	v_fmac_f32_e32 v144, v102, v102
	v_add_f32_e32 v143, v143, v144
	v_mul_f32_e32 v144, v97, v97
	v_mul_f32_e32 v145, v99, v99
	v_fmac_f32_e32 v144, v96, v96
	v_fmac_f32_e32 v145, v98, v98
	v_add_f32_e32 v144, v144, v145
	v_add_f32_e32 v143, v143, v144
	v_mov_b32_e32 v199, v143
	v_mul_f32_e32 v143, v93, v93
	s_waitcnt lgkmcnt(0)
	v_mul_f32_e32 v144, v95, v95
	v_fmac_f32_e32 v143, v92, v92
	v_fmac_f32_e32 v144, v94, v94
	v_add_f32_e32 v143, v143, v144
	v_mul_f32_e32 v144, v89, v89
	v_mul_f32_e32 v145, v91, v91
	v_fmac_f32_e32 v144, v88, v88
	v_fmac_f32_e32 v145, v90, v90
	v_add_f32_e32 v144, v144, v145
	v_add_f32_e32 v143, v143, v144
	v_mov_b32_e32 v200, v143
	v_mul_f32_e32 v143, v85, v85
	s_waitcnt lgkmcnt(0)
	v_mul_f32_e32 v144, v87, v87
	v_fmac_f32_e32 v143, v84, v84
	v_fmac_f32_e32 v144, v86, v86
	v_add_f32_e32 v143, v143, v144
	v_mul_f32_e32 v144, v81, v81
	v_mul_f32_e32 v145, v83, v83
	v_fmac_f32_e32 v144, v80, v80
	v_fmac_f32_e32 v145, v82, v82
	v_add_f32_e32 v144, v144, v145
	v_add_f32_e32 v143, v143, v144
	v_mov_b32_e32 v201, v143
	v_mul_f32_e32 v143, v77, v77
	s_waitcnt lgkmcnt(0)
	v_mul_f32_e32 v144, v79, v79
	v_fmac_f32_e32 v143, v76, v76
	v_fmac_f32_e32 v144, v78, v78
	v_add_f32_e32 v143, v143, v144
	v_mul_f32_e32 v144, v73, v73
	v_mul_f32_e32 v145, v75, v75
	v_fmac_f32_e32 v144, v72, v72
	v_fmac_f32_e32 v145, v74, v74
	v_add_f32_e32 v144, v144, v145
	v_add_f32_e32 v143, v143, v144
	v_mov_b32_e32 v202, v143
	v_mul_f32_e32 v143, v69, v69
	s_waitcnt lgkmcnt(0)
	v_mul_f32_e32 v144, v71, v71
	v_fmac_f32_e32 v143, v68, v68
	v_fmac_f32_e32 v144, v70, v70
	v_add_f32_e32 v143, v143, v144
	v_mul_f32_e32 v144, v65, v65
	v_mul_f32_e32 v145, v67, v67
	v_fmac_f32_e32 v144, v64, v64
	v_fmac_f32_e32 v145, v66, v66
	v_add_f32_e32 v144, v144, v145
	v_add_f32_e32 v143, v143, v144
	v_mov_b32_e32 v203, v143
	v_mul_f32_e32 v143, v61, v61
	s_waitcnt lgkmcnt(0)
	v_mul_f32_e32 v144, v63, v63
	v_fmac_f32_e32 v143, v60, v60
	v_fmac_f32_e32 v144, v62, v62
	v_add_f32_e32 v143, v143, v144
	v_mul_f32_e32 v144, v57, v57
	v_mul_f32_e32 v145, v59, v59
	v_fmac_f32_e32 v144, v56, v56
	v_fmac_f32_e32 v145, v58, v58
	v_add_f32_e32 v144, v144, v145
	v_add_f32_e32 v143, v143, v144
	v_mov_b32_e32 v204, v143
	v_mul_f32_e32 v143, v53, v53
	s_waitcnt lgkmcnt(0)
	v_mul_f32_e32 v144, v55, v55
	v_fmac_f32_e32 v143, v52, v52
	v_fmac_f32_e32 v144, v54, v54
	v_add_f32_e32 v143, v143, v144
	v_mul_f32_e32 v144, v49, v49
	v_mul_f32_e32 v145, v51, v51
	v_fmac_f32_e32 v144, v48, v48
	v_fmac_f32_e32 v145, v50, v50
	v_add_f32_e32 v144, v144, v145
	v_add_f32_e32 v143, v143, v144
	v_mov_b32_e32 v205, v143
	v_mul_f32_e32 v143, v45, v45
	s_waitcnt lgkmcnt(0)
	v_mul_f32_e32 v144, v47, v47
	v_fmac_f32_e32 v143, v44, v44
	v_fmac_f32_e32 v144, v46, v46
	v_add_f32_e32 v143, v143, v144
	v_mul_f32_e32 v144, v41, v41
	v_mul_f32_e32 v145, v43, v43
	v_fmac_f32_e32 v144, v40, v40
	v_fmac_f32_e32 v145, v42, v42
	v_add_f32_e32 v144, v144, v145
	v_add_f32_e32 v143, v143, v144
	v_mov_b32_e32 v206, v143
	v_mul_f32_e32 v143, v37, v37
	s_waitcnt lgkmcnt(0)
	v_mul_f32_e32 v144, v39, v39
	v_fmac_f32_e32 v143, v36, v36
	v_fmac_f32_e32 v144, v38, v38
	v_add_f32_e32 v143, v143, v144
	v_mul_f32_e32 v144, v33, v33
	v_mul_f32_e32 v145, v35, v35
	v_fmac_f32_e32 v144, v32, v32
	v_fmac_f32_e32 v145, v34, v34
	v_add_f32_e32 v144, v144, v145
	v_add_f32_e32 v143, v143, v144
	v_mov_b32_e32 v207, v143
	v_mul_f32_e32 v143, v29, v29
	s_waitcnt lgkmcnt(0)
	v_mul_f32_e32 v144, v31, v31
	v_fmac_f32_e32 v143, v28, v28
	v_fmac_f32_e32 v144, v30, v30
	v_add_f32_e32 v143, v143, v144
	v_mul_f32_e32 v144, v25, v25
	v_mul_f32_e32 v145, v27, v27
	v_fmac_f32_e32 v144, v24, v24
	v_fmac_f32_e32 v145, v26, v26
	v_add_f32_e32 v144, v144, v145
	v_add_f32_e32 v143, v143, v144
	v_mov_b32_e32 v208, v143
	v_mul_f32_e32 v143, v21, v21
	s_waitcnt lgkmcnt(0)
	v_mul_f32_e32 v144, v23, v23
	v_fmac_f32_e32 v143, v20, v20
	v_fmac_f32_e32 v144, v22, v22
	v_add_f32_e32 v143, v143, v144
	v_mul_f32_e32 v144, v17, v17
	v_mul_f32_e32 v145, v19, v19
	v_fmac_f32_e32 v144, v16, v16
	v_fmac_f32_e32 v145, v18, v18
	v_add_f32_e32 v144, v144, v145
	v_add_f32_e32 v143, v143, v144
	v_mov_b32_e32 v209, v143
	v_mul_f32_e32 v143, v13, v13
	s_waitcnt lgkmcnt(0)
	v_mul_f32_e32 v144, v15, v15
	v_fmac_f32_e32 v143, v12, v12
	v_fmac_f32_e32 v144, v14, v14
	v_add_f32_e32 v143, v143, v144
	v_mul_f32_e32 v144, v9, v9
	v_mul_f32_e32 v145, v11, v11
	v_fmac_f32_e32 v144, v8, v8
	v_fmac_f32_e32 v145, v10, v10
	v_add_f32_e32 v144, v144, v145
	v_add_f32_e32 v143, v143, v144
	v_mov_b32_e32 v210, v143
	v_mul_f32_e32 v143, v5, v5
	s_waitcnt lgkmcnt(0)
	v_mul_f32_e32 v144, v7, v7
	v_fmac_f32_e32 v143, v4, v4
	v_fmac_f32_e32 v144, v6, v6
	v_add_f32_e32 v143, v143, v144
	v_mul_f32_e32 v144, v1, v1
	v_mul_f32_e32 v145, v3, v3
	v_fmac_f32_e32 v144, v0, v0
	v_fmac_f32_e32 v145, v2, v2
	v_add_f32_e32 v144, v144, v145
	v_add_f32_e32 v143, v143, v144
	v_mov_b32_e32 v211, v143
	ds_bpermute_b32 v212, v132, v196
	ds_bpermute_b32 v213, v132, v197
	ds_bpermute_b32 v214, v132, v198
	ds_bpermute_b32 v215, v132, v199
	ds_bpermute_b32 v216, v132, v200
	ds_bpermute_b32 v217, v132, v201
	ds_bpermute_b32 v218, v132, v202
	ds_bpermute_b32 v219, v132, v203
	s_waitcnt lgkmcnt(0)
	v_add_f32_e32 v196, v196, v212
	v_add_f32_e32 v197, v197, v213
	v_add_f32_e32 v198, v198, v214
	v_add_f32_e32 v199, v199, v215
	v_add_f32_e32 v200, v200, v216
	v_add_f32_e32 v201, v201, v217
	v_add_f32_e32 v202, v202, v218
	v_add_f32_e32 v203, v203, v219
	ds_bpermute_b32 v212, v142, v196
	ds_bpermute_b32 v213, v142, v197
	ds_bpermute_b32 v214, v142, v198
	ds_bpermute_b32 v215, v142, v199
	ds_bpermute_b32 v216, v142, v200
	ds_bpermute_b32 v217, v142, v201
	ds_bpermute_b32 v218, v142, v202
	ds_bpermute_b32 v219, v142, v203
	s_waitcnt lgkmcnt(0)
	v_add_f32_e32 v196, v196, v212
	v_add_f32_e32 v197, v197, v213
	v_add_f32_e32 v198, v198, v214
	v_add_f32_e32 v199, v199, v215
	v_add_f32_e32 v200, v200, v216
	v_add_f32_e32 v201, v201, v217
	v_add_f32_e32 v202, v202, v218
	v_add_f32_e32 v203, v203, v219
	ds_bpermute_b32 v220, v132, v204
	ds_bpermute_b32 v221, v132, v205
	ds_bpermute_b32 v222, v132, v206
	ds_bpermute_b32 v223, v132, v207
	ds_bpermute_b32 v224, v132, v208
	ds_bpermute_b32 v225, v132, v209
	ds_bpermute_b32 v226, v132, v210
	ds_bpermute_b32 v227, v132, v211
	s_waitcnt lgkmcnt(0)
	v_add_f32_e32 v204, v204, v220
	v_add_f32_e32 v205, v205, v221
	v_add_f32_e32 v206, v206, v222
	v_add_f32_e32 v207, v207, v223
	v_add_f32_e32 v208, v208, v224
	v_add_f32_e32 v209, v209, v225
	v_add_f32_e32 v210, v210, v226
	v_add_f32_e32 v211, v211, v227
	ds_bpermute_b32 v220, v142, v204
	ds_bpermute_b32 v221, v142, v205
	ds_bpermute_b32 v222, v142, v206
	ds_bpermute_b32 v223, v142, v207
	ds_bpermute_b32 v224, v142, v208
	ds_bpermute_b32 v225, v142, v209
	ds_bpermute_b32 v226, v142, v210
	ds_bpermute_b32 v227, v142, v211
	s_waitcnt lgkmcnt(0)
	v_add_f32_e32 v204, v204, v220
	v_add_f32_e32 v205, v205, v221
	v_add_f32_e32 v206, v206, v222
	v_add_f32_e32 v207, v207, v223
	v_add_f32_e32 v208, v208, v224
	v_add_f32_e32 v209, v209, v225
	v_add_f32_e32 v210, v210, v226
	v_add_f32_e32 v211, v211, v227
	s_and_saveexec_b64 s[0:1], s[6:7]
	ds_write_b32 v152, v196
	ds_write_b32 v152, v197 offset:16
	ds_write_b32 v153, v198
	ds_write_b32 v153, v199 offset:16
	ds_write_b32 v154, v200
	ds_write_b32 v154, v201 offset:16
	ds_write_b32 v155, v202
	ds_write_b32 v155, v203 offset:16
	ds_write_b32 v156, v204
	ds_write_b32 v156, v205 offset:16
	ds_write_b32 v157, v206
	ds_write_b32 v157, v207 offset:16
	ds_write_b32 v158, v208
	ds_write_b32 v158, v209 offset:16
	ds_write_b32 v159, v210
	ds_write_b32 v159, v211 offset:16
	s_or_b64 exec, exec, s[0:1]
	s_cmp_lt_u32 s20, 16
	s_cselect_b64 vcc, -1, 0
	s_and_b64 s[0:1], vcc, exec
	v_readlane_b32 s0, v250, 21
	s_cselect_b32 s20, s50, s52
	v_readlane_b32 s1, v250, 22
	s_cselect_b32 s2, s51, s53
	s_cselect_b32 s1, s1, s95
	s_cselect_b32 s0, s0, s94
	s_add_u32 s22, s20, s43
	s_waitcnt lgkmcnt(0)
	s_barrier
	s_addc_u32 s23, s2, 0
	v_lshlrev_b32_e32 v132, 2, v134
	global_load_dwordx4 v[144:147], v132, s[22:23]
	global_load_dwordx4 v[148:151], v132, s[22:23] offset:16
	ds_read_b128 v[168:171], v137
	v_cndmask_b32_e32 v172, 1.0, v166, vcc
	v_lshlrev_b32_e32 v132, 1, v136
	s_waitcnt lgkmcnt(0)
	v_mov_b32_e32 v142, v169
	v_mov_b32_e32 v143, v170
	v_mov_b32_e32 v169, v171
	v_pk_add_f32 v[142:143], v[142:143], v[168:169]
	s_nop 0
	v_add_f32_e32 v142, v142, v143
	v_fmamk_f32 v142, v142, 0x3c000000, v163
	v_rsq_f32_e32 v168, v142
	v_lshl_add_u64 v[142:143], s[0:1], 0, v[132:133]
	v_lshlrev_b32_e32 v132, 1, v134
	v_lshl_add_u64 v[142:143], v[142:143], 0, v[132:133]
	v_pk_mul_f32 v[170:171], v[124:125], v[168:169] op_sel_hi:[1,0]
	v_pk_mul_f32 v[174:175], v[126:127], v[168:169] op_sel_hi:[1,0]
	v_pk_mul_f32 v[176:177], v[120:121], v[168:169] op_sel_hi:[1,0]
	v_pk_mul_f32 v[168:169], v[122:123], v[168:169] op_sel_hi:[1,0]
	s_lshl_b32 s0, s15, 3
	s_lshr_b32 s1, s13, 5
	s_or_b32 s22, s1, s0
	s_ashr_i32 s23, s22, 31
	s_lshl_b64 s[22:23], s[22:23], 10
	s_or_b32 s2, s1, 4
	s_or_b32 s13, s0, 0x80
	s_waitcnt vmcnt(0)
	v_pk_mul_f32 v[124:125], v[172:173], v[146:147] op_sel_hi:[0,1]
	v_pk_mul_f32 v[126:127], v[172:173], v[144:145] op_sel_hi:[0,1]
	v_pk_mul_f32 v[120:121], v[172:173], v[150:151] op_sel_hi:[0,1]
	v_pk_mul_f32 v[122:123], v[172:173], v[148:149] op_sel_hi:[0,1]
	v_pk_mul_f32 v[146:147], v[124:125], v[174:175]
	v_pk_mul_f32 v[144:145], v[126:127], v[170:171]
	v_pk_mul_f32 v[148:149], v[120:121], v[168:169]
	v_pk_mul_f32 v[150:151], v[122:123], v[176:177]
	v_cvt_pk_bf16_f32 v144, v144, v145
	v_cvt_pk_bf16_f32 v145, v146, v147
	s_nop 0
	v_cvt_pk_bf16_f32 v146, v150, v151
	v_cvt_pk_bf16_f32 v147, v148, v149
	ds_read_b128 v[148:151], v137 offset:16
	s_waitcnt lgkmcnt(0)
	v_mov_b32_e32 v168, v149
	v_mov_b32_e32 v169, v150
	v_mov_b32_e32 v149, v151
	v_pk_add_f32 v[148:149], v[168:169], v[148:149]
	s_nop 0
	v_add_f32_e32 v132, v148, v149
	v_fmamk_f32 v132, v132, 0x3c000000, v163
	v_rsq_f32_e32 v132, v132
	v_lshl_add_u64 v[148:149], v[142:143], 0, s[22:23]
	global_store_dwordx4 v[148:149], v[144:147], off
	s_or_b32 s22, s2, s0
	v_pk_mul_f32 v[116:117], v[116:117], v[132:133] op_sel_hi:[1,0]
	v_pk_mul_f32 v[118:119], v[118:119], v[132:133] op_sel_hi:[1,0]
	v_pk_mul_f32 v[112:113], v[112:113], v[132:133] op_sel_hi:[1,0]
	v_pk_mul_f32 v[114:115], v[114:115], v[132:133] op_sel_hi:[1,0]
	v_pk_mul_f32 v[118:119], v[124:125], v[118:119]
	v_pk_mul_f32 v[116:117], v[126:127], v[116:117]
	v_pk_mul_f32 v[144:145], v[120:121], v[114:115]
	v_pk_mul_f32 v[114:115], v[122:123], v[112:113]
	v_cvt_pk_bf16_f32 v112, v116, v117
	v_cvt_pk_bf16_f32 v113, v118, v119
	s_ashr_i32 s23, s22, 31
	v_cvt_pk_bf16_f32 v114, v114, v115
	v_cvt_pk_bf16_f32 v115, v144, v145
	ds_read_b128 v[116:119], v137 offset:512
	s_lshl_b64 s[22:23], s[22:23], 10
	s_waitcnt lgkmcnt(0)
	v_mov_b32_e32 v144, v117
	v_mov_b32_e32 v145, v118
	v_mov_b32_e32 v117, v119
	v_pk_add_f32 v[116:117], v[144:145], v[116:117]
	v_lshl_add_u64 v[118:119], v[142:143], 0, s[22:23]
	v_add_f32_e32 v116, v116, v117
	v_fmamk_f32 v116, v116, 0x3c000000, v163
	v_rsq_f32_e32 v116, v116
	global_store_dwordx4 v[118:119], v[112:115], off
	s_or_b32 s22, s13, s1
	s_ashr_i32 s23, s22, 31
	v_pk_mul_f32 v[108:109], v[108:109], v[116:117] op_sel_hi:[1,0]
	v_pk_mul_f32 v[110:111], v[110:111], v[116:117] op_sel_hi:[1,0]
	v_pk_mul_f32 v[104:105], v[104:105], v[116:117] op_sel_hi:[1,0]
	v_pk_mul_f32 v[106:107], v[106:107], v[116:117] op_sel_hi:[1,0]
	v_pk_mul_f32 v[110:111], v[124:125], v[110:111]
	v_pk_mul_f32 v[108:109], v[126:127], v[108:109]
	v_pk_mul_f32 v[112:113], v[120:121], v[106:107]
	v_pk_mul_f32 v[106:107], v[122:123], v[104:105]
	v_cvt_pk_bf16_f32 v104, v108, v109
	v_cvt_pk_bf16_f32 v105, v110, v111
	s_lshl_b64 s[22:23], s[22:23], 10
	v_cvt_pk_bf16_f32 v106, v106, v107
	v_cvt_pk_bf16_f32 v107, v112, v113
	ds_read_b128 v[108:111], v137 offset:528
	s_waitcnt lgkmcnt(0)
	v_mov_b32_e32 v112, v109
	v_mov_b32_e32 v113, v110
	v_mov_b32_e32 v109, v111
	v_pk_add_f32 v[108:109], v[112:113], v[108:109]
	v_lshl_add_u64 v[110:111], v[142:143], 0, s[22:23]
	v_add_f32_e32 v108, v108, v109
	v_fmamk_f32 v108, v108, 0x3c000000, v163
	v_rsq_f32_e32 v108, v108
	global_store_dwordx4 v[110:111], v[104:107], off
	s_or_b32 s22, s2, s13
	s_ashr_i32 s23, s22, 31
	v_pk_mul_f32 v[100:101], v[100:101], v[108:109] op_sel_hi:[1,0]
	v_pk_mul_f32 v[102:103], v[102:103], v[108:109] op_sel_hi:[1,0]
	v_pk_mul_f32 v[96:97], v[96:97], v[108:109] op_sel_hi:[1,0]
	v_pk_mul_f32 v[98:99], v[98:99], v[108:109] op_sel_hi:[1,0]
	v_pk_mul_f32 v[102:103], v[124:125], v[102:103]
	v_pk_mul_f32 v[100:101], v[126:127], v[100:101]
	v_pk_mul_f32 v[104:105], v[120:121], v[98:99]
	v_pk_mul_f32 v[98:99], v[122:123], v[96:97]
	v_cvt_pk_bf16_f32 v96, v100, v101
	v_cvt_pk_bf16_f32 v97, v102, v103
	s_lshl_b64 s[22:23], s[22:23], 10
	v_cvt_pk_bf16_f32 v98, v98, v99
	v_cvt_pk_bf16_f32 v99, v104, v105
	ds_read_b128 v[100:103], v137 offset:1024
	s_or_b32 s13, s0, 0x100
	s_waitcnt lgkmcnt(0)
	v_mov_b32_e32 v104, v101
	v_mov_b32_e32 v105, v102
	v_mov_b32_e32 v101, v103
	v_pk_add_f32 v[100:101], v[104:105], v[100:101]
	v_lshl_add_u64 v[102:103], v[142:143], 0, s[22:23]
	v_add_f32_e32 v100, v100, v101
	v_fmamk_f32 v100, v100, 0x3c000000, v163
	v_rsq_f32_e32 v100, v100
	global_store_dwordx4 v[102:103], v[96:99], off
	s_or_b32 s22, s13, s1
	s_ashr_i32 s23, s22, 31
	v_pk_mul_f32 v[92:93], v[92:93], v[100:101] op_sel_hi:[1,0]
	v_pk_mul_f32 v[94:95], v[94:95], v[100:101] op_sel_hi:[1,0]
	v_pk_mul_f32 v[88:89], v[88:89], v[100:101] op_sel_hi:[1,0]
	v_pk_mul_f32 v[90:91], v[90:91], v[100:101] op_sel_hi:[1,0]
	v_pk_mul_f32 v[94:95], v[124:125], v[94:95]
	v_pk_mul_f32 v[92:93], v[126:127], v[92:93]
	v_pk_mul_f32 v[96:97], v[120:121], v[90:91]
	v_pk_mul_f32 v[90:91], v[122:123], v[88:89]
	v_cvt_pk_bf16_f32 v88, v92, v93
	v_cvt_pk_bf16_f32 v89, v94, v95
	s_lshl_b64 s[22:23], s[22:23], 10
	v_cvt_pk_bf16_f32 v90, v90, v91
	v_cvt_pk_bf16_f32 v91, v96, v97
	ds_read_b128 v[92:95], v137 offset:1040
	s_waitcnt lgkmcnt(0)
	v_mov_b32_e32 v96, v93
	v_mov_b32_e32 v97, v94
	v_mov_b32_e32 v93, v95
	v_pk_add_f32 v[92:93], v[96:97], v[92:93]
	v_lshl_add_u64 v[94:95], v[142:143], 0, s[22:23]
	v_add_f32_e32 v92, v92, v93
	v_fmamk_f32 v92, v92, 0x3c000000, v163
	v_rsq_f32_e32 v92, v92
	global_store_dwordx4 v[94:95], v[88:91], off
	s_or_b32 s22, s2, s13
	s_ashr_i32 s23, s22, 31
	v_pk_mul_f32 v[84:85], v[84:85], v[92:93] op_sel_hi:[1,0]
	v_pk_mul_f32 v[86:87], v[86:87], v[92:93] op_sel_hi:[1,0]
	v_pk_mul_f32 v[80:81], v[80:81], v[92:93] op_sel_hi:[1,0]
	v_pk_mul_f32 v[82:83], v[82:83], v[92:93] op_sel_hi:[1,0]
	v_pk_mul_f32 v[86:87], v[124:125], v[86:87]
	v_pk_mul_f32 v[84:85], v[126:127], v[84:85]
	v_pk_mul_f32 v[88:89], v[120:121], v[82:83]
	v_pk_mul_f32 v[82:83], v[122:123], v[80:81]
	v_cvt_pk_bf16_f32 v80, v84, v85
	v_cvt_pk_bf16_f32 v81, v86, v87
	s_lshl_b64 s[22:23], s[22:23], 10
	v_cvt_pk_bf16_f32 v82, v82, v83
	v_cvt_pk_bf16_f32 v83, v88, v89
	ds_read_b128 v[84:87], v137 offset:1536
	s_or_b32 s13, s0, 0x180
	s_waitcnt lgkmcnt(0)
	v_mov_b32_e32 v88, v85
	v_mov_b32_e32 v89, v86
	v_mov_b32_e32 v85, v87
	v_pk_add_f32 v[84:85], v[88:89], v[84:85]
	v_lshl_add_u64 v[86:87], v[142:143], 0, s[22:23]
	v_add_f32_e32 v84, v84, v85
	v_fmamk_f32 v84, v84, 0x3c000000, v163
	v_rsq_f32_e32 v84, v84
	global_store_dwordx4 v[86:87], v[80:83], off
	s_or_b32 s22, s13, s1
	s_ashr_i32 s23, s22, 31
	v_pk_mul_f32 v[76:77], v[76:77], v[84:85] op_sel_hi:[1,0]
	v_pk_mul_f32 v[78:79], v[78:79], v[84:85] op_sel_hi:[1,0]
	v_pk_mul_f32 v[72:73], v[72:73], v[84:85] op_sel_hi:[1,0]
	v_pk_mul_f32 v[74:75], v[74:75], v[84:85] op_sel_hi:[1,0]
	v_pk_mul_f32 v[78:79], v[124:125], v[78:79]
	v_pk_mul_f32 v[76:77], v[126:127], v[76:77]
	v_pk_mul_f32 v[80:81], v[120:121], v[74:75]
	v_pk_mul_f32 v[74:75], v[122:123], v[72:73]
	v_cvt_pk_bf16_f32 v72, v76, v77
	v_cvt_pk_bf16_f32 v73, v78, v79
	s_lshl_b64 s[22:23], s[22:23], 10
	v_cvt_pk_bf16_f32 v74, v74, v75
	v_cvt_pk_bf16_f32 v75, v80, v81
	ds_read_b128 v[76:79], v137 offset:1552
	s_waitcnt lgkmcnt(0)
	v_mov_b32_e32 v80, v77
	v_mov_b32_e32 v81, v78
	v_mov_b32_e32 v77, v79
	v_pk_add_f32 v[76:77], v[80:81], v[76:77]
	v_lshl_add_u64 v[78:79], v[142:143], 0, s[22:23]
	v_add_f32_e32 v76, v76, v77
	v_fmamk_f32 v76, v76, 0x3c000000, v163
	v_rsq_f32_e32 v76, v76
	global_store_dwordx4 v[78:79], v[72:75], off
	s_or_b32 s22, s2, s13
	s_ashr_i32 s23, s22, 31
	v_pk_mul_f32 v[68:69], v[68:69], v[76:77] op_sel_hi:[1,0]
	v_pk_mul_f32 v[70:71], v[70:71], v[76:77] op_sel_hi:[1,0]
	v_pk_mul_f32 v[64:65], v[64:65], v[76:77] op_sel_hi:[1,0]
	v_pk_mul_f32 v[66:67], v[66:67], v[76:77] op_sel_hi:[1,0]
	v_pk_mul_f32 v[70:71], v[124:125], v[70:71]
	v_pk_mul_f32 v[68:69], v[126:127], v[68:69]
	v_pk_mul_f32 v[72:73], v[120:121], v[66:67]
	v_pk_mul_f32 v[66:67], v[122:123], v[64:65]
	v_cvt_pk_bf16_f32 v64, v68, v69
	v_cvt_pk_bf16_f32 v65, v70, v71
	s_lshl_b64 s[22:23], s[22:23], 10
	v_cvt_pk_bf16_f32 v66, v66, v67
	v_cvt_pk_bf16_f32 v67, v72, v73
	ds_read_b128 v[68:71], v137 offset:4096
	s_add_i32 s13, s0, 0x400
	s_waitcnt lgkmcnt(0)
	v_mov_b32_e32 v72, v69
	v_mov_b32_e32 v73, v70
	v_mov_b32_e32 v69, v71
	v_pk_add_f32 v[68:69], v[72:73], v[68:69]
	v_lshl_add_u64 v[70:71], v[142:143], 0, s[22:23]
	v_add_f32_e32 v68, v68, v69
	v_fmamk_f32 v68, v68, 0x3c000000, v163
	v_rsq_f32_e32 v68, v68
	global_store_dwordx4 v[70:71], v[64:67], off
	s_or_b32 s22, s13, s1
	s_ashr_i32 s23, s22, 31
	v_pk_mul_f32 v[60:61], v[60:61], v[68:69] op_sel_hi:[1,0]
	v_pk_mul_f32 v[62:63], v[62:63], v[68:69] op_sel_hi:[1,0]
	v_pk_mul_f32 v[56:57], v[56:57], v[68:69] op_sel_hi:[1,0]
	v_pk_mul_f32 v[58:59], v[58:59], v[68:69] op_sel_hi:[1,0]
	v_pk_mul_f32 v[62:63], v[124:125], v[62:63]
	v_pk_mul_f32 v[60:61], v[126:127], v[60:61]
	v_pk_mul_f32 v[64:65], v[120:121], v[58:59]
	v_pk_mul_f32 v[58:59], v[122:123], v[56:57]
	v_cvt_pk_bf16_f32 v56, v60, v61
	v_cvt_pk_bf16_f32 v57, v62, v63
	s_lshl_b64 s[22:23], s[22:23], 10
	v_cvt_pk_bf16_f32 v58, v58, v59
	v_cvt_pk_bf16_f32 v59, v64, v65
	ds_read_b128 v[60:63], v137 offset:4112
	s_waitcnt lgkmcnt(0)
	v_mov_b32_e32 v64, v61
	v_mov_b32_e32 v65, v62
	v_mov_b32_e32 v61, v63
	v_pk_add_f32 v[60:61], v[64:65], v[60:61]
	v_lshl_add_u64 v[62:63], v[142:143], 0, s[22:23]
	v_add_f32_e32 v60, v60, v61
	v_fmamk_f32 v60, v60, 0x3c000000, v163
	v_rsq_f32_e32 v60, v60
	global_store_dwordx4 v[62:63], v[56:59], off
	s_or_b32 s22, s2, s13
	s_ashr_i32 s23, s22, 31
	v_pk_mul_f32 v[52:53], v[52:53], v[60:61] op_sel_hi:[1,0]
	v_pk_mul_f32 v[54:55], v[54:55], v[60:61] op_sel_hi:[1,0]
	v_pk_mul_f32 v[48:49], v[48:49], v[60:61] op_sel_hi:[1,0]
	v_pk_mul_f32 v[50:51], v[50:51], v[60:61] op_sel_hi:[1,0]
	v_pk_mul_f32 v[54:55], v[124:125], v[54:55]
	v_pk_mul_f32 v[52:53], v[126:127], v[52:53]
	v_pk_mul_f32 v[56:57], v[120:121], v[50:51]
	v_pk_mul_f32 v[50:51], v[122:123], v[48:49]
	v_cvt_pk_bf16_f32 v48, v52, v53
	v_cvt_pk_bf16_f32 v49, v54, v55
	s_lshl_b64 s[22:23], s[22:23], 10
	v_cvt_pk_bf16_f32 v50, v50, v51
	v_cvt_pk_bf16_f32 v51, v56, v57
	ds_read_b128 v[52:55], v137 offset:4608
	s_add_i32 s13, s0, 0x480
	s_waitcnt lgkmcnt(0)
	v_mov_b32_e32 v56, v53
	v_mov_b32_e32 v57, v54
	v_mov_b32_e32 v53, v55
	v_pk_add_f32 v[52:53], v[56:57], v[52:53]
	v_lshl_add_u64 v[54:55], v[142:143], 0, s[22:23]
	v_add_f32_e32 v52, v52, v53
	v_fmamk_f32 v52, v52, 0x3c000000, v163
	v_rsq_f32_e32 v52, v52
	global_store_dwordx4 v[54:55], v[48:51], off
	s_or_b32 s22, s13, s1
	s_ashr_i32 s23, s22, 31
	v_pk_mul_f32 v[44:45], v[44:45], v[52:53] op_sel_hi:[1,0]
	v_pk_mul_f32 v[46:47], v[46:47], v[52:53] op_sel_hi:[1,0]
	v_pk_mul_f32 v[40:41], v[40:41], v[52:53] op_sel_hi:[1,0]
	v_pk_mul_f32 v[42:43], v[42:43], v[52:53] op_sel_hi:[1,0]
	v_pk_mul_f32 v[46:47], v[124:125], v[46:47]
	v_pk_mul_f32 v[44:45], v[126:127], v[44:45]
	v_pk_mul_f32 v[48:49], v[120:121], v[42:43]
	v_pk_mul_f32 v[42:43], v[122:123], v[40:41]
	v_cvt_pk_bf16_f32 v40, v44, v45
	v_cvt_pk_bf16_f32 v41, v46, v47
	s_lshl_b64 s[22:23], s[22:23], 10
	v_cvt_pk_bf16_f32 v42, v42, v43
	v_cvt_pk_bf16_f32 v43, v48, v49
	ds_read_b128 v[44:47], v137 offset:4624
	s_waitcnt lgkmcnt(0)
	v_mov_b32_e32 v48, v45
	v_mov_b32_e32 v49, v46
	v_mov_b32_e32 v45, v47
	v_pk_add_f32 v[44:45], v[48:49], v[44:45]
	v_lshl_add_u64 v[46:47], v[142:143], 0, s[22:23]
	v_add_f32_e32 v44, v44, v45
	v_fmamk_f32 v44, v44, 0x3c000000, v163
	v_rsq_f32_e32 v44, v44
	global_store_dwordx4 v[46:47], v[40:43], off
	s_or_b32 s22, s2, s13
	s_ashr_i32 s23, s22, 31
	v_pk_mul_f32 v[36:37], v[36:37], v[44:45] op_sel_hi:[1,0]
	v_pk_mul_f32 v[38:39], v[38:39], v[44:45] op_sel_hi:[1,0]
	v_pk_mul_f32 v[32:33], v[32:33], v[44:45] op_sel_hi:[1,0]
	v_pk_mul_f32 v[34:35], v[34:35], v[44:45] op_sel_hi:[1,0]
	v_pk_mul_f32 v[38:39], v[124:125], v[38:39]
	v_pk_mul_f32 v[36:37], v[126:127], v[36:37]
	v_pk_mul_f32 v[40:41], v[120:121], v[34:35]
	v_pk_mul_f32 v[34:35], v[122:123], v[32:33]
	v_cvt_pk_bf16_f32 v32, v36, v37
	v_cvt_pk_bf16_f32 v33, v38, v39
	s_lshl_b64 s[22:23], s[22:23], 10
	v_cvt_pk_bf16_f32 v34, v34, v35
	v_cvt_pk_bf16_f32 v35, v40, v41
	ds_read_b128 v[36:39], v137 offset:5120
	s_add_i32 s13, s0, 0x500
	s_waitcnt lgkmcnt(0)
	v_mov_b32_e32 v40, v37
	v_mov_b32_e32 v41, v38
	v_mov_b32_e32 v37, v39
	v_pk_add_f32 v[36:37], v[40:41], v[36:37]
	v_lshl_add_u64 v[38:39], v[142:143], 0, s[22:23]
	v_add_f32_e32 v36, v36, v37
	v_fmamk_f32 v36, v36, 0x3c000000, v163
	v_rsq_f32_e32 v36, v36
	global_store_dwordx4 v[38:39], v[32:35], off
	s_or_b32 s22, s13, s1
	s_ashr_i32 s23, s22, 31
	v_pk_mul_f32 v[28:29], v[28:29], v[36:37] op_sel_hi:[1,0]
	v_pk_mul_f32 v[30:31], v[30:31], v[36:37] op_sel_hi:[1,0]
	v_pk_mul_f32 v[24:25], v[24:25], v[36:37] op_sel_hi:[1,0]
	v_pk_mul_f32 v[26:27], v[26:27], v[36:37] op_sel_hi:[1,0]
	v_pk_mul_f32 v[30:31], v[124:125], v[30:31]
	v_pk_mul_f32 v[28:29], v[126:127], v[28:29]
	v_pk_mul_f32 v[32:33], v[120:121], v[26:27]
	v_pk_mul_f32 v[26:27], v[122:123], v[24:25]
	v_cvt_pk_bf16_f32 v24, v28, v29
	v_cvt_pk_bf16_f32 v25, v30, v31
	s_lshl_b64 s[22:23], s[22:23], 10
	v_cvt_pk_bf16_f32 v26, v26, v27
	v_cvt_pk_bf16_f32 v27, v32, v33
	ds_read_b128 v[28:31], v137 offset:5136
	s_waitcnt lgkmcnt(0)
	v_mov_b32_e32 v32, v29
	v_mov_b32_e32 v33, v30
	v_mov_b32_e32 v29, v31
	v_pk_add_f32 v[28:29], v[32:33], v[28:29]
	v_lshl_add_u64 v[30:31], v[142:143], 0, s[22:23]
	v_add_f32_e32 v28, v28, v29
	v_fmamk_f32 v28, v28, 0x3c000000, v163
	v_rsq_f32_e32 v28, v28
	global_store_dwordx4 v[30:31], v[24:27], off
	s_or_b32 s22, s2, s13
	s_ashr_i32 s23, s22, 31
	v_pk_mul_f32 v[20:21], v[20:21], v[28:29] op_sel_hi:[1,0]
	v_pk_mul_f32 v[22:23], v[22:23], v[28:29] op_sel_hi:[1,0]
	v_pk_mul_f32 v[16:17], v[16:17], v[28:29] op_sel_hi:[1,0]
	v_pk_mul_f32 v[18:19], v[18:19], v[28:29] op_sel_hi:[1,0]
	v_pk_mul_f32 v[22:23], v[124:125], v[22:23]
	v_pk_mul_f32 v[20:21], v[126:127], v[20:21]
	v_pk_mul_f32 v[24:25], v[120:121], v[18:19]
	v_pk_mul_f32 v[18:19], v[122:123], v[16:17]
	v_cvt_pk_bf16_f32 v16, v20, v21
	v_cvt_pk_bf16_f32 v17, v22, v23
	s_lshl_b64 s[22:23], s[22:23], 10
	v_cvt_pk_bf16_f32 v18, v18, v19
	v_cvt_pk_bf16_f32 v19, v24, v25
	ds_read_b128 v[20:23], v137 offset:5632
	v_lshl_add_u64 v[24:25], v[142:143], 0, s[22:23]
	global_store_dwordx4 v[24:25], v[16:19], off
	s_add_i32 s13, s0, 0x580
	s_or_b32 s0, s13, s1
	s_waitcnt lgkmcnt(0)
	v_mov_b32_e32 v26, v21
	v_mov_b32_e32 v27, v22
	v_mov_b32_e32 v21, v23
	v_pk_add_f32 v[20:21], v[26:27], v[20:21]
	s_ashr_i32 s1, s0, 31
	v_add_f32_e32 v20, v20, v21
	v_fmamk_f32 v20, v20, 0x3c000000, v163
	v_rsq_f32_e32 v20, v20
	s_lshl_b64 s[0:1], s[0:1], 10
	v_pk_mul_f32 v[12:13], v[12:13], v[20:21] op_sel_hi:[1,0]
	v_pk_mul_f32 v[14:15], v[14:15], v[20:21] op_sel_hi:[1,0]
	v_pk_mul_f32 v[8:9], v[8:9], v[20:21] op_sel_hi:[1,0]
	v_pk_mul_f32 v[10:11], v[10:11], v[20:21] op_sel_hi:[1,0]
	v_pk_mul_f32 v[14:15], v[124:125], v[14:15]
	v_pk_mul_f32 v[12:13], v[126:127], v[12:13]
	v_pk_mul_f32 v[16:17], v[120:121], v[10:11]
	v_pk_mul_f32 v[10:11], v[122:123], v[8:9]
	v_cvt_pk_bf16_f32 v8, v12, v13
	v_cvt_pk_bf16_f32 v9, v14, v15
	s_nop 0
	v_cvt_pk_bf16_f32 v10, v10, v11
	v_cvt_pk_bf16_f32 v11, v16, v17
	ds_read_b128 v[12:15], v137 offset:5648
	v_lshl_add_u64 v[16:17], v[142:143], 0, s[0:1]
	global_store_dwordx4 v[16:17], v[8:11], off
	s_or_b32 s0, s2, s13
	s_ashr_i32 s1, s0, 31
	s_waitcnt lgkmcnt(0)
	v_mov_b32_e32 v8, v13
	v_mov_b32_e32 v9, v14
	v_mov_b32_e32 v13, v15
	v_pk_add_f32 v[8:9], v[8:9], v[12:13]
	s_lshl_b64 s[0:1], s[0:1], 10
	v_add_f32_e32 v8, v8, v9
	v_fmamk_f32 v8, v8, 0x3c000000, v163
	v_rsq_f32_e32 v8, v8
	v_lshl_add_u64 v[10:11], v[142:143], 0, s[0:1]
	v_pk_mul_f32 v[0:1], v[0:1], v[8:9] op_sel_hi:[1,0]
	v_pk_mul_f32 v[2:3], v[2:3], v[8:9] op_sel_hi:[1,0]
	v_pk_mul_f32 v[4:5], v[4:5], v[8:9] op_sel_hi:[1,0]
	v_pk_mul_f32 v[6:7], v[6:7], v[8:9] op_sel_hi:[1,0]
	v_pk_mul_f32 v[8:9], v[120:121], v[2:3]
	v_pk_mul_f32 v[2:3], v[122:123], v[0:1]
	v_pk_mul_f32 v[6:7], v[124:125], v[6:7]
	v_pk_mul_f32 v[4:5], v[126:127], v[4:5]
	s_nop 0
	v_cvt_pk_bf16_f32 v0, v4, v5
	v_cvt_pk_bf16_f32 v1, v6, v7
	v_cvt_pk_bf16_f32 v2, v2, v3
	v_cvt_pk_bf16_f32 v3, v8, v9
	global_store_dwordx4 v[10:11], v[0:3], off
	s_andn2_b64 vcc, exec, s[4:5]
	s_mov_b64 s[0:1], -1
	s_cbranch_vccnz .LBB0_86
